# v15 + KIND1 windowed-attention loop: S accumulators start from MFMA C=0 (16 v_mov_b64 removed), 16-op v_max3 row-max tree
# baseline (speedup 1.0000x reference)
.LBB0_694:
	s_and_b64 s[20:21], s[20:21], exec
	s_cselect_b32 s21, s45, s46
	s_and_b32 s20, 1, s45
	s_cmp_gt_i32 s21, 3
	s_cselect_b64 s[46:47], -1, 0
	s_and_b64 s[46:47], s[30:31], s[46:47]
	s_mov_b32 s53, s52
	s_cmp_eq_u32 s20, 1
	s_mov_b32 s54, s52
	s_mov_b32 s55, s52
	s_mov_b32 s56, s52
	s_mov_b32 s57, s52
	s_mov_b32 s58, s52
	s_mov_b32 s59, s52
	s_mov_b32 s60, s52
	s_mov_b32 s61, s52
	s_mov_b32 s62, s52
	s_mov_b32 s63, s52
	s_mov_b32 s64, s52
	s_mov_b32 s65, s52
	s_mov_b32 s66, s52
	s_mov_b32 s67, s52
	s_cselect_b32 s20, 0xa000, 0
	v_or_b32_e32 v0, s20, v99
	v_add_u32_e32 v144, v0, v103
	v_add_u32_e32 v145, v0, v104
	v_add_u32_e32 v146, v0, v105
	v_add_u32_e32 v0, v0, v106
	ds_read_b128 v[120:123], v144 offset:0
	ds_read_b128 v[124:127], v144 offset:4096
	ds_read_b128 v[128:131], v145 offset:0
	ds_read_b128 v[132:135], v145 offset:4096
	ds_read_b128 v[136:139], v146 offset:0
	ds_read_b128 v[140:143], v146 offset:4096
	s_waitcnt lgkmcnt(5)
	v_mfma_f32_32x32x16_bf16 v[50:65], v[120:123], v[66:69], 0
	ds_read_b128 v[120:123], v0 offset:0
	s_waitcnt lgkmcnt(5)
	v_mfma_f32_32x32x16_bf16 v[34:49], v[124:127], v[66:69], 0
	ds_read_b128 v[124:127], v0 offset:4096
	s_waitcnt lgkmcnt(5)
	v_mfma_f32_32x32x16_bf16 v[50:65], v[128:131], v[70:73], v[50:65]
	s_waitcnt lgkmcnt(4)
	v_mfma_f32_32x32x16_bf16 v[34:49], v[132:135], v[70:73], v[34:49]
	s_waitcnt lgkmcnt(3)
	v_mfma_f32_32x32x16_bf16 v[50:65], v[136:139], v[74:77], v[50:65]
	s_waitcnt lgkmcnt(2)
	v_mfma_f32_32x32x16_bf16 v[34:49], v[140:143], v[74:77], v[34:49]
	s_waitcnt lgkmcnt(1)
	v_mfma_f32_32x32x16_bf16 v[50:65], v[120:123], v[78:81], v[50:65]
	s_waitcnt lgkmcnt(0)
	v_mfma_f32_32x32x16_bf16 v[34:49], v[124:127], v[78:81], v[34:49]
	s_nop 15
	s_nop 3

	s_andn2_b64 vcc, exec, s[46:47]
	s_cbranch_vccnz .LBB0_696
	s_lshl_b32 s21, s21, 6
	v_subrev_u32_e32 v0, s21, v100
	v_add_u32_e32 v120, v0, v101
	v_sub_u32_e32 v121, 0, v120
	v_max_i32_e32 v120, v120, v121
	v_cmp_lt_u32_e32 vcc, s2, v120
	v_add_u32_e32 v120, v0, v107
	v_sub_u32_e32 v121, 0, v120
	v_max_i32_e32 v120, v120, v121
	s_movk_i32 s4, 0x81
	v_cndmask_b32_e32 v50, v50, v225, vcc
	v_cmp_gt_u32_e32 vcc, s4, v120
	v_add_u32_e32 v120, v0, v108
	v_sub_u32_e32 v121, 0, v120
	v_max_i32_e32 v120, v120, v121
	v_cndmask_b32_e32 v51, v225, v51, vcc
	v_cmp_gt_u32_e32 vcc, s4, v120
	v_add_u32_e32 v120, v0, v109
	v_sub_u32_e32 v121, 0, v120
	v_max_i32_e32 v120, v120, v121
	v_cndmask_b32_e32 v52, v225, v52, vcc
	v_cmp_gt_u32_e32 vcc, s4, v120
	v_add_u32_e32 v120, v0, v110
	v_sub_u32_e32 v121, 0, v120
	v_max_i32_e32 v120, v120, v121
	v_cndmask_b32_e32 v53, v225, v53, vcc
	v_cmp_gt_u32_e32 vcc, s4, v120
	v_add_u32_e32 v120, v0, v111
	v_sub_u32_e32 v121, 0, v120
	v_max_i32_e32 v120, v120, v121
	v_cndmask_b32_e32 v54, v225, v54, vcc
	v_cmp_gt_u32_e32 vcc, s4, v120
	v_add_u32_e32 v120, v0, v112
	v_sub_u32_e32 v121, 0, v120
	v_max_i32_e32 v120, v120, v121
	v_add_u32_e32 v0, v0, v113
	v_cndmask_b32_e32 v55, v225, v55, vcc
	v_cmp_gt_u32_e32 vcc, s4, v120
	v_sub_u32_e32 v120, 0, v0
	v_max_i32_e32 v0, v0, v120
	s_or_b32 s45, s21, 16
	v_cndmask_b32_e32 v56, v225, v56, vcc
	v_cmp_gt_u32_e32 vcc, s4, v0
	v_subrev_u32_e32 v0, s45, v100
	v_add_u32_e32 v120, v0, v101
	v_sub_u32_e32 v121, 0, v120
	v_max_i32_e32 v120, v120, v121
	v_cndmask_b32_e32 v57, v225, v57, vcc
	v_cmp_gt_u32_e32 vcc, s4, v120
	v_add_u32_e32 v120, v0, v107
	v_sub_u32_e32 v121, 0, v120
	v_max_i32_e32 v120, v120, v121
	v_cndmask_b32_e32 v58, v225, v58, vcc
	v_cmp_gt_u32_e32 vcc, s4, v120
	v_add_u32_e32 v120, v0, v108
	v_sub_u32_e32 v121, 0, v120
	v_max_i32_e32 v120, v120, v121
	v_cndmask_b32_e32 v59, v225, v59, vcc
	v_cmp_gt_u32_e32 vcc, s4, v120
	v_add_u32_e32 v120, v0, v109
	v_sub_u32_e32 v121, 0, v120
	v_max_i32_e32 v120, v120, v121
	v_cndmask_b32_e32 v60, v225, v60, vcc
	v_cmp_gt_u32_e32 vcc, s4, v120
	v_add_u32_e32 v120, v0, v110
	v_sub_u32_e32 v121, 0, v120
	v_max_i32_e32 v120, v120, v121
	v_cndmask_b32_e32 v61, v225, v61, vcc
	v_cmp_gt_u32_e32 vcc, s4, v120
	v_add_u32_e32 v120, v0, v111
	v_sub_u32_e32 v121, 0, v120
	v_max_i32_e32 v120, v120, v121
	v_cndmask_b32_e32 v62, v225, v62, vcc
	v_cmp_gt_u32_e32 vcc, s4, v120
	v_add_u32_e32 v120, v0, v112
	v_sub_u32_e32 v121, 0, v120
	v_max_i32_e32 v120, v120, v121
	v_add_u32_e32 v0, v0, v113
	v_cndmask_b32_e32 v63, v225, v63, vcc
	v_cmp_gt_u32_e32 vcc, s4, v120
	v_sub_u32_e32 v120, 0, v0
	v_max_i32_e32 v0, v0, v120
	s_or_b32 s45, s21, 32
	v_cndmask_b32_e32 v64, v225, v64, vcc
	v_cmp_gt_u32_e32 vcc, s4, v0
	v_subrev_u32_e32 v0, s45, v100
	v_add_u32_e32 v120, v0, v101
	v_sub_u32_e32 v121, 0, v120
	v_max_i32_e32 v120, v120, v121
	v_cndmask_b32_e32 v65, v225, v65, vcc
	v_cmp_gt_u32_e32 vcc, s4, v120
	v_add_u32_e32 v120, v0, v107
	v_sub_u32_e32 v121, 0, v120
	v_max_i32_e32 v120, v120, v121
	v_cndmask_b32_e32 v34, v225, v34, vcc
	v_cmp_gt_u32_e32 vcc, s4, v120
	v_add_u32_e32 v120, v0, v108
	v_sub_u32_e32 v121, 0, v120
	v_max_i32_e32 v120, v120, v121
	v_cndmask_b32_e32 v35, v225, v35, vcc
	v_cmp_gt_u32_e32 vcc, s4, v120
	v_add_u32_e32 v120, v0, v109
	v_sub_u32_e32 v121, 0, v120
	v_max_i32_e32 v120, v120, v121
	v_cndmask_b32_e32 v36, v225, v36, vcc
	v_cmp_gt_u32_e32 vcc, s4, v120
	v_add_u32_e32 v120, v0, v110
	v_sub_u32_e32 v121, 0, v120
	v_max_i32_e32 v120, v120, v121
	v_cndmask_b32_e32 v37, v225, v37, vcc
	v_cmp_gt_u32_e32 vcc, s4, v120
	v_add_u32_e32 v120, v0, v111
	v_sub_u32_e32 v121, 0, v120
	v_max_i32_e32 v120, v120, v121
	v_cndmask_b32_e32 v38, v225, v38, vcc
	v_cmp_gt_u32_e32 vcc, s4, v120
	v_add_u32_e32 v120, v0, v112
	v_sub_u32_e32 v121, 0, v120
	v_max_i32_e32 v120, v120, v121
	v_add_u32_e32 v0, v0, v113
	v_cndmask_b32_e32 v39, v225, v39, vcc
	v_cmp_gt_u32_e32 vcc, s4, v120
	v_sub_u32_e32 v120, 0, v0
	v_max_i32_e32 v0, v0, v120
	s_or_b32 s21, s21, 48
	v_cndmask_b32_e32 v40, v225, v40, vcc
	v_cmp_gt_u32_e32 vcc, s4, v0
	v_subrev_u32_e32 v0, s21, v100
	v_add_u32_e32 v120, v0, v101
	v_sub_u32_e32 v121, 0, v120
	v_max_i32_e32 v120, v120, v121
	v_cndmask_b32_e32 v41, v225, v41, vcc
	v_cmp_gt_u32_e32 vcc, s4, v120
	v_add_u32_e32 v120, v0, v107
	v_sub_u32_e32 v121, 0, v120
	v_max_i32_e32 v120, v120, v121
	v_cndmask_b32_e32 v42, v225, v42, vcc
	v_cmp_gt_u32_e32 vcc, s4, v120
	v_add_u32_e32 v120, v0, v108
	v_sub_u32_e32 v121, 0, v120
	v_max_i32_e32 v120, v120, v121
	v_cndmask_b32_e32 v43, v225, v43, vcc
	v_cmp_gt_u32_e32 vcc, s4, v120
	v_add_u32_e32 v120, v0, v109
	v_sub_u32_e32 v121, 0, v120
	v_max_i32_e32 v120, v120, v121
	v_cndmask_b32_e32 v44, v225, v44, vcc
	v_cmp_gt_u32_e32 vcc, s4, v120
	v_add_u32_e32 v120, v0, v110
	v_sub_u32_e32 v121, 0, v120
	v_max_i32_e32 v120, v120, v121
	v_cndmask_b32_e32 v45, v225, v45, vcc
	v_cmp_gt_u32_e32 vcc, s4, v120
	v_add_u32_e32 v120, v0, v111
	v_sub_u32_e32 v121, 0, v120
	v_max_i32_e32 v120, v120, v121
	v_cndmask_b32_e32 v46, v225, v46, vcc
	v_cmp_gt_u32_e32 vcc, s4, v120
	v_add_u32_e32 v120, v0, v112
	v_sub_u32_e32 v121, 0, v120
	v_max_i32_e32 v120, v120, v121
	v_add_u32_e32 v0, v0, v113
	v_cndmask_b32_e32 v47, v225, v47, vcc
	v_cmp_gt_u32_e32 vcc, s4, v120
	v_sub_u32_e32 v120, 0, v0
	v_max_i32_e32 v0, v0, v120
	v_cndmask_b32_e32 v48, v225, v48, vcc
	v_cmp_gt_u32_e32 vcc, s4, v0
	s_nop 1
	v_cndmask_b32_e32 v49, v225, v49, vcc
.LBB0_696:
	s_mov_b32 s4, 0xf149f2ca
	v_max3_f32 v0, v50, v51, s4
	v_max3_f32 v120, v52, v53, v54
	v_max3_f32 v121, v55, v56, v57
	v_max3_f32 v122, v58, v59, v60
	v_max3_f32 v0, v0, v61, v62
	v_max3_f32 v120, v120, v63, v64
	v_max3_f32 v121, v121, v65, v34
	v_max3_f32 v122, v122, v35, v36
	v_max3_f32 v0, v0, v37, v38
	v_max3_f32 v120, v120, v39, v40
	v_max3_f32 v121, v121, v41, v42
	v_max3_f32 v122, v122, v43, v44
	v_max3_f32 v0, v0, v45, v46
	v_max3_f32 v120, v120, v47, v48
	v_max3_f32 v121, v121, v49, v122
	v_max3_f32 v0, v0, v120, v121
	v_mov_b32_e32 v120, v0
	s_nop 1
	v_permlane32_swap_b32_e32 v0, v120
	v_max3_f32 v120, v119, v0, v120
	v_mul_f32_e32 v0, 0xbe38aa3b, v120
	v_fmamk_f32 v50, v50, 0x3e38aa3b, v0
	v_exp_f32_e32 v50, v50
	v_fmamk_f32 v51, v51, 0x3e38aa3b, v0
	v_exp_f32_e32 v51, v51
	v_fmamk_f32 v52, v52, 0x3e38aa3b, v0
	v_exp_f32_e32 v52, v52
	v_fmamk_f32 v53, v53, 0x3e38aa3b, v0
	v_sub_f32_e32 v119, v119, v120
	v_exp_f32_e32 v53, v53
	v_fmamk_f32 v54, v54, 0x3e38aa3b, v0
	v_mul_f32_e32 v123, 0x3e38aa3b, v119
	v_add_f32_e32 v119, 0, v50
	v_exp_f32_e32 v54, v54
	v_fmamk_f32 v55, v55, 0x3e38aa3b, v0
	v_add_f32_e32 v119, v51, v119
	v_exp_f32_e32 v55, v55
	v_fmamk_f32 v56, v56, 0x3e38aa3b, v0
	v_add_f32_e32 v119, v52, v119
	v_exp_f32_e32 v56, v56
	v_fmamk_f32 v57, v57, 0x3e38aa3b, v0
	v_add_f32_e32 v121, v53, v119
	v_exp_f32_e32 v119, v57
	v_add_f32_e32 v57, v54, v121
	v_add_f32_e32 v57, v55, v57
	v_add_f32_e32 v57, v56, v57
	v_add_f32_e32 v121, v119, v57
	v_fmamk_f32 v57, v58, 0x3e38aa3b, v0
	v_exp_f32_e32 v57, v57
	v_fmamk_f32 v58, v59, 0x3e38aa3b, v0
	v_exp_f32_e32 v58, v58
	v_fmamk_f32 v59, v60, 0x3e38aa3b, v0
	v_exp_f32_e32 v59, v59
	v_fmamk_f32 v60, v61, 0x3e38aa3b, v0
	v_exp_f32_e32 v60, v60
	v_add_f32_e32 v61, v57, v121
	v_add_f32_e32 v61, v58, v61
	v_add_f32_e32 v61, v59, v61
	v_add_f32_e32 v121, v60, v61
	v_fmamk_f32 v61, v62, 0x3e38aa3b, v0
	v_exp_f32_e32 v61, v61
	v_fmamk_f32 v62, v63, 0x3e38aa3b, v0
	v_exp_f32_e32 v62, v62
	v_fmamk_f32 v63, v64, 0x3e38aa3b, v0
	v_exp_f32_e32 v63, v63
	v_fmamk_f32 v64, v65, 0x3e38aa3b, v0
	v_exp_f32_e32 v64, v64
	v_fmamk_f32 v34, v34, 0x3e38aa3b, v0
	v_add_f32_e32 v65, v61, v121
	v_exp_f32_e32 v34, v34
	v_fmamk_f32 v35, v35, 0x3e38aa3b, v0
	v_add_f32_e32 v65, v62, v65
	v_exp_f32_e32 v35, v35
	v_fmamk_f32 v36, v36, 0x3e38aa3b, v0
	v_add_f32_e32 v65, v63, v65
	v_exp_f32_e32 v36, v36
	v_fmamk_f32 v37, v37, 0x3e38aa3b, v0
	v_add_f32_e32 v121, v64, v65
	v_exp_f32_e32 v65, v37
	v_fmamk_f32 v38, v38, 0x3e38aa3b, v0
	v_add_f32_e32 v37, v34, v121
	v_exp_f32_e32 v121, v38
	v_fmamk_f32 v38, v39, 0x3e38aa3b, v0
	v_add_f32_e32 v37, v35, v37
	v_exp_f32_e32 v39, v38
	v_fmamk_f32 v38, v40, 0x3e38aa3b, v0
	v_add_f32_e32 v37, v36, v37
	v_exp_f32_e32 v40, v38
	v_fmamk_f32 v38, v41, 0x3e38aa3b, v0
	v_add_f32_e32 v37, v65, v37
	v_exp_f32_e32 v122, v38
	v_fmamk_f32 v38, v42, 0x3e38aa3b, v0
	v_add_f32_e32 v37, v121, v37
	v_exp_f32_e32 v41, v38
	v_fmamk_f32 v38, v43, 0x3e38aa3b, v0
	v_add_f32_e32 v37, v39, v37
	v_exp_f32_e32 v42, v38
	v_fmamk_f32 v38, v44, 0x3e38aa3b, v0
	v_add_f32_e32 v37, v40, v37
	v_exp_f32_e32 v43, v38
	v_fmamk_f32 v38, v45, 0x3e38aa3b, v0
	v_add_f32_e32 v37, v122, v37
	v_exp_f32_e32 v44, v38
	v_fmamk_f32 v38, v46, 0x3e38aa3b, v0
	v_add_f32_e32 v37, v41, v37
	v_exp_f32_e32 v45, v38
	v_fmamk_f32 v38, v47, 0x3e38aa3b, v0
	v_add_f32_e32 v37, v42, v37
	v_exp_f32_e32 v46, v38
	v_fmamk_f32 v38, v48, 0x3e38aa3b, v0
	v_add_f32_e32 v37, v43, v37
	v_exp_f32_e32 v47, v38
	v_fmac_f32_e32 v0, 0x3e38aa3b, v49
	v_add_f32_e32 v37, v44, v37
	v_exp_f32_e32 v48, v0
	v_add_f32_e32 v0, v45, v37
	v_add_f32_e32 v0, v46, v0
	v_add_f32_e32 v0, v47, v0
	v_add_f32_e32 v37, v48, v0
	v_exp_f32_e32 v0, v123
	v_mov_b32_e32 v38, v37
	s_nop 1
	v_permlane32_swap_b32_e32 v37, v38
	v_cmp_neq_f32_e32 vcc, 1.0, v0
	s_cbranch_vccz .LBB0_698
	v_pk_mul_f32 v[32:33], v[32:33], v[0:1] op_sel_hi:[1,0]
	v_pk_mul_f32 v[30:31], v[30:31], v[0:1] op_sel_hi:[1,0]
	v_pk_mul_f32 v[28:29], v[28:29], v[0:1] op_sel_hi:[1,0]
	v_pk_mul_f32 v[26:27], v[26:27], v[0:1] op_sel_hi:[1,0]
	v_pk_mul_f32 v[24:25], v[24:25], v[0:1] op_sel_hi:[1,0]
	v_pk_mul_f32 v[22:23], v[22:23], v[0:1] op_sel_hi:[1,0]
	v_pk_mul_f32 v[20:21], v[20:21], v[0:1] op_sel_hi:[1,0]
	v_pk_mul_f32 v[18:19], v[18:19], v[0:1] op_sel_hi:[1,0]
	v_pk_mul_f32 v[16:17], v[16:17], v[0:1] op_sel_hi:[1,0]
	v_pk_mul_f32 v[14:15], v[14:15], v[0:1] op_sel_hi:[1,0]
	v_pk_mul_f32 v[12:13], v[12:13], v[0:1] op_sel_hi:[1,0]
	v_pk_mul_f32 v[10:11], v[10:11], v[0:1] op_sel_hi:[1,0]
	v_pk_mul_f32 v[8:9], v[8:9], v[0:1] op_sel_hi:[1,0]
	v_pk_mul_f32 v[6:7], v[6:7], v[0:1] op_sel_hi:[1,0]
	v_pk_mul_f32 v[4:5], v[4:5], v[0:1] op_sel_hi:[1,0]
	v_pk_mul_f32 v[2:3], v[2:3], v[0:1] op_sel_hi:[1,0]
